# nt hint: + scan output stores
# baseline (speedup 1.0000x reference)
.LBB0_1438:
	s_and_b32 s4, s90, 0x60
	s_cmp_lg_u32 s4, 0
	s_cbranch_scc1 .LBB0_1440
	v_lshl_add_u32 v86, s42, 5, v152
	v_mul_hi_i32_i24_e32 v87, 0x1800, v86
	v_mul_i32_i24_e32 v86, 0x1800, v86
	v_lshl_add_u64 v[86:87], v[154:155], 0, v[86:87]
	v_cvt_pk_bf16_f32 v82, v82, v83
	v_cvt_pk_bf16_f32 v83, v84, v85
	global_store_dwordx2 v[86:87], v[82:83], off nt
	v_cvt_pk_bf16_f32 v78, v78, v79
	v_cvt_pk_bf16_f32 v79, v80, v81
	v_add_co_u32_e32 v80, vcc, 0x18000, v86
	s_nop 1
	v_addc_co_u32_e32 v81, vcc, 0, v87, vcc
	global_store_dwordx2 v[80:81], v[78:79], off nt

.LBB0_1453:
	s_and_b32 s10, s90, 0x60
	s_cmp_lg_u32 s10, 0
	s_cbranch_scc1 .LBB0_1455
	v_lshl_add_u32 v118, s41, 5, v152
	v_mul_hi_i32_i24_e32 v119, 0x1800, v118
	v_mul_i32_i24_e32 v118, 0x1800, v118
	v_lshl_add_u64 v[118:119], v[154:155], 0, v[118:119]
	v_cvt_pk_bf16_f32 v114, v114, v115
	v_cvt_pk_bf16_f32 v115, v116, v117
	global_store_dwordx2 v[118:119], v[114:115], off nt
	v_cvt_pk_bf16_f32 v110, v110, v111
	v_cvt_pk_bf16_f32 v111, v112, v113
	v_add_co_u32_e32 v112, vcc, 0x18000, v118
	s_nop 1
	v_addc_co_u32_e32 v113, vcc, 0, v119, vcc
	global_store_dwordx2 v[112:113], v[110:111], off nt

.LBB0_1467:
	s_and_b32 s10, s90, 0x60
	s_cmp_lg_u32 s10, 0
	s_cbranch_scc1 .LBB0_1469
	v_lshl_add_u32 v118, s37, 5, v152
	v_mul_hi_i32_i24_e32 v119, 0x1800, v118
	v_mul_i32_i24_e32 v118, 0x1800, v118
	v_lshl_add_u64 v[118:119], v[154:155], 0, v[118:119]
	v_cvt_pk_bf16_f32 v114, v114, v115
	v_cvt_pk_bf16_f32 v115, v116, v117
	global_store_dwordx2 v[118:119], v[114:115], off nt
	v_cvt_pk_bf16_f32 v110, v110, v111
	v_cvt_pk_bf16_f32 v111, v112, v113
	v_add_co_u32_e32 v112, vcc, 0x18000, v118
	s_nop 1
	v_addc_co_u32_e32 v113, vcc, 0, v119, vcc
	global_store_dwordx2 v[112:113], v[110:111], off nt

.LBB0_1481:
	s_and_b32 s10, s90, 0x60
	s_cmp_lg_u32 s10, 0
	s_cbranch_scc1 .LBB0_1483
	v_lshl_add_u32 v118, s28, 5, v152
	v_mul_hi_i32_i24_e32 v119, 0x1800, v118
	v_mul_i32_i24_e32 v118, 0x1800, v118
	v_lshl_add_u64 v[118:119], v[154:155], 0, v[118:119]
	v_cvt_pk_bf16_f32 v114, v114, v115
	v_cvt_pk_bf16_f32 v115, v116, v117
	global_store_dwordx2 v[118:119], v[114:115], off nt
	v_cvt_pk_bf16_f32 v110, v110, v111
	v_cvt_pk_bf16_f32 v111, v112, v113
	v_add_co_u32_e32 v112, vcc, 0x18000, v118
	s_nop 1
	v_addc_co_u32_e32 v113, vcc, 0, v119, vcc
	global_store_dwordx2 v[112:113], v[110:111], off nt

.LBB0_1498:
	s_and_b32 s8, s90, 0x60
	s_cmp_lg_u32 s8, 0
	s_cbranch_scc1 .LBB0_1500
	s_movk_i32 s9, 0x2080
	s_and_b64 s[10:11], s[18:19], exec
	s_cselect_b32 s9, s9, 0x2060
	v_add_u32_e32 v118, s9, v152
	v_mul_hi_i32_i24_e32 v119, 0x1800, v118
	v_mul_i32_i24_e32 v118, 0x1800, v118
	v_lshl_add_u64 v[118:119], v[154:155], 0, v[118:119]
	v_cvt_pk_bf16_f32 v114, v114, v115
	v_cvt_pk_bf16_f32 v115, v116, v117
	global_store_dwordx2 v[118:119], v[114:115], off nt
	v_cvt_pk_bf16_f32 v110, v110, v111
	v_cvt_pk_bf16_f32 v111, v112, v113
	v_add_co_u32_e32 v112, vcc, 0x18000, v118
	s_nop 1
	v_addc_co_u32_e32 v113, vcc, 0, v119, vcc
	global_store_dwordx2 v[112:113], v[110:111], off nt

.LBB0_1533:
	s_andn2_b64 vcc, exec, s[8:9]
	s_cbranch_vccnz .LBB0_1502
	s_add_i32 s28, s36, 4
	s_cmp_lt_u32 s35, 8
	s_cselect_b32 s26, 0x100, -8
	s_add_i32 s29, s26, s35
	s_and_b64 s[26:27], s[18:19], exec
	s_cselect_b32 s26, s29, s28
	s_lshl_b32 s26, s26, 5
	s_ashr_i32 s27, s26, 31
	v_lshl_add_u64 v[118:119], v[152:153], 0, s[26:27]
	v_mad_u64_u32 v[120:121], s[26:27], v118, s37, v[154:155]
	v_mov_b32_e32 v118, v121
	v_mad_u64_u32 v[118:119], s[26:27], v119, s37, v[118:119]
	v_mov_b32_e32 v121, v118
	v_cvt_pk_bf16_f32 v114, v114, v115
	v_cvt_pk_bf16_f32 v115, v116, v117
	global_store_dwordx2 v[120:121], v[114:115], off nt
	v_cvt_pk_bf16_f32 v110, v110, v111
	v_cvt_pk_bf16_f32 v111, v112, v113
	v_add_co_u32_e32 v112, vcc, 0x18000, v120
	s_nop 1
	v_addc_co_u32_e32 v113, vcc, 0, v118, vcc
	global_store_dwordx2 v[112:113], v[110:111], off nt
	s_branch .LBB0_1502
